# v23
# baseline (speedup 1.0000x reference)
; template <int EPI>
; __device__ __forceinline__ void gemm_phase(const u16* __restrict__ A, const u16* __restrict__ Bt, const int K,
;                                            const int nN, char* shm, const EpiArgs& ea) {
;     ...
;   const int wid = __builtin_amdgcn_readfirstlane(tid >> 6);
;   const int lane = tid & 63;
;   const int wr = wid >> 2, wc = wid & 3, fr = lane & 15, fq = lane >> 4;
.LBB0_14:
	v_readfirstlane_b32 s98, v174
	s_nop 3
	s_cmp_lt_u32 s98, 0x100
	s_cbranch_scc1 .Lprio_skip
	s_setprio 1
